# v20: v19 + hgrn_item (P5) next-sub-chunk loads issued back to back, packed after with counted waits
# speedup vs baseline: 1.0036x; 1.0036x over previous
; #define LAS __attribute__((address_space(3)))
; template <bool OUT> DI void hgrn_item(LAS unsigned char* lds, bf16_t* proj, float* hst, float* hdv, const float* normw, int item, bool dry) {
;     ...
;         *(LAS u32x4*)(VT + d * TP + tq * 16) = (u32x4){rvv[0], rvv[1], rvv[2], rvv[3]};
;         *(LAS u32x4*)(VT + d * TP + tq * 16 + 8) = (u32x4){rvv[4], rvv[5], rvv[6], rvv[7]};
;         if (sc < 3) HG_LOAD(sc + 1);
.LBB0_1171:
	s_cmp_eq_u32 s34, 0x258000
	ds_write_b128 v77, v[34:37] offset:53248
	ds_write_b128 v77, v[38:41] offset:53264
	s_cbranch_scc1 .LBB0_1173
	v_lshl_add_u64 v[34:35], v[94:95], 0, s[34:35]
	v_add_co_u32_e32 v36, vcc, 0xc8000, v34
	s_nop 1
	v_addc_co_u32_e32 v37, vcc, 0, v35, vcc
	v_add_co_u32_e32 v38, vcc, 0xcb000, v34
	s_nop 1
	v_addc_co_u32_e32 v39, vcc, 0, v35, vcc
	v_add_co_u32_e32 v40, vcc, 0xcc000, v34
	s_nop 1
	v_addc_co_u32_e32 v41, vcc, 0, v35, vcc
	v_add_co_u32_e32 v58, vcc, 0xce000, v34
	s_nop 1
	v_addc_co_u32_e32 v59, vcc, 0, v35, vcc
	global_load_ushort v62, v[36:37], off offset:2560
	global_load_ushort v63, v[38:39], off offset:3072
	global_load_ushort v64, v[36:37], off offset:3584
	global_load_ushort v65, v[40:41], off
	global_load_ushort v66, v[58:59], off offset:3584
	global_load_ushort v67, v[58:59], off offset:2560
	global_load_ushort v68, v[38:39], off offset:2048
	global_load_ushort v69, v[36:37], off offset:1536
	v_add_co_u32_e32 v36, vcc, 0xd2000, v34
	v_addc_co_u32_e32 v37, vcc, 0, v35, vcc
	v_add_co_u32_e32 v38, vcc, 0xcf000, v34
	v_addc_co_u32_e32 v39, vcc, 0, v35, vcc
	v_add_co_u32_e32 v40, vcc, 0xd1000, v34
	s_nop 1
	v_addc_co_u32_e32 v41, vcc, 0, v35, vcc
	v_add_co_u32_e32 v58, vcc, 0xd5000, v34
	s_nop 1
	v_addc_co_u32_e32 v59, vcc, 0, v35, vcc
	v_add_co_u32_e32 v60, vcc, 0xd8000, v34
	s_nop 1
	v_addc_co_u32_e32 v61, vcc, 0, v35, vcc
	global_load_ushort v70, v[36:37], off
	global_load_ushort v71, v[38:39], off offset:512
	global_load_ushort v72, v[40:41], off offset:3072
	global_load_ushort v73, v[58:59], off offset:512
	global_load_ushort v100, v[60:61], off offset:1024
	global_load_ushort v101, v[58:59], off offset:1536
	global_load_ushort v102, v[60:61], off
	global_load_ushort v103, v[36:37], off offset:1024
	v_add_co_u32_e32 v36, vcc, 0xd4000, v34
	v_addc_co_u32_e32 v37, vcc, 0, v35, vcc
	v_add_co_u32_e32 v38, vcc, 0xdb000, v34
	v_addc_co_u32_e32 v39, vcc, 0, v35, vcc
	v_add_co_u32_e32 v40, vcc, 0xde000, v34
	v_addc_co_u32_e32 v41, vcc, 0, v35, vcc
	global_load_ushort v130, v[60:61], off offset:2048
	global_load_ushort v132, v[36:37], off offset:3584
	global_load_ushort v134, v[38:39], off offset:1536
	global_load_ushort v135, v[40:41], off offset:2048
	global_load_ushort v136, v[38:39], off offset:2560
	global_load_ushort v137, v[40:41], off offset:3072
	global_load_ushort v138, v[40:41], off offset:1024
	global_load_ushort v139, v[38:39], off offset:512
	v_add_co_u32_e32 v36, vcc, 0xe1000, v34
	v_addc_co_u32_e32 v37, vcc, 0, v35, vcc
	v_add_co_u32_e32 v38, vcc, 0xe4000, v34
	s_nop 1
	v_addc_co_u32_e32 v39, vcc, 0, v35, vcc
	v_add_co_u32_e32 v40, vcc, 0xe5000, v34
	s_nop 1
	v_addc_co_u32_e32 v41, vcc, 0, v35, vcc
	v_add_co_u32_e32 v58, vcc, 0xe7000, v34
	s_nop 1
	v_addc_co_u32_e32 v59, vcc, 0, v35, vcc
	global_load_ushort v140, v[36:37], off offset:2560
	global_load_ushort v141, v[38:39], off offset:3072
	global_load_ushort v142, v[36:37], off offset:3584
	global_load_ushort v143, v[40:41], off
	global_load_ushort v144, v[58:59], off offset:3584
	global_load_ushort v145, v[58:59], off offset:2560
	global_load_ushort v146, v[38:39], off offset:2048
	global_load_ushort v147, v[36:37], off offset:1536
	v_add_co_u32_e32 v36, vcc, 0xeb000, v34
	v_addc_co_u32_e32 v37, vcc, 0, v35, vcc
	v_add_co_u32_e32 v38, vcc, 0xe8000, v34
	s_nop 1
	v_addc_co_u32_e32 v39, vcc, 0, v35, vcc
	v_add_co_u32_e32 v40, vcc, 0xea000, v34
	s_nop 1
	v_addc_co_u32_e32 v41, vcc, 0, v35, vcc
	v_add_co_u32_e32 v58, vcc, 0xee000, v34
	s_nop 1
	v_addc_co_u32_e32 v59, vcc, 0, v35, vcc
	v_add_co_u32_e32 v60, vcc, 0xf1000, v34
	s_nop 1
	v_addc_co_u32_e32 v61, vcc, 0, v35, vcc
	global_load_ushort v148, v[36:37], off
	global_load_ushort v149, v[38:39], off offset:512
	s_nop 0
	global_load_ushort v40, v[40:41], off offset:3072
	s_nop 0
	global_load_ushort v41, v[58:59], off offset:512
	global_load_ushort v150, v[60:61], off offset:1024
	s_nop 0
	global_load_ushort v58, v[58:59], off offset:1536
	s_nop 0
	global_load_ushort v59, v[60:61], off
	global_load_ushort v151, v[36:37], off offset:1024
	v_add_co_u32_e32 v36, vcc, 0xed000, v34
	s_nop 1
	v_addc_co_u32_e32 v37, vcc, 0, v35, vcc
	v_add_co_u32_e32 v38, vcc, 0xf4000, v34
	s_nop 1
	v_addc_co_u32_e32 v39, vcc, 0, v35, vcc
	v_add_co_u32_e32 v34, vcc, 0xf7000, v34
	s_nop 1
	v_addc_co_u32_e32 v35, vcc, 0, v35, vcc
	global_load_ushort v60, v[60:61], off offset:2048
	s_nop 0
	global_load_ushort v61, v[36:37], off offset:3584
	global_load_ushort v152, v[38:39], off offset:1536
	global_load_ushort v153, v[34:35], off offset:2048
	global_load_ushort v154, v[38:39], off offset:2560
	global_load_ushort v155, v[34:35], off offset:3072
	global_load_ushort v156, v[34:35], off offset:1024
	global_load_ushort v157, v[38:39], off offset:512
	s_waitcnt vmcnt(46)
	v_lshl_or_b32 v129, v63, 16, v62
	s_waitcnt vmcnt(40)
	v_lshl_or_b32 v127, v68, 16, v69
	s_waitcnt vmcnt(39)
	v_lshl_or_b32 v131, v70, 16, v66
	s_waitcnt vmcnt(37)
	v_lshl_or_b32 v128, v72, 16, v67
	s_waitcnt vmcnt(35)
	v_lshl_or_b32 v133, v100, 16, v73
	s_waitcnt vmcnt(28)
	v_lshl_or_b32 v135, v135, 16, v134
	s_waitcnt vmcnt(16)
	v_lshl_or_b32 v134, v146, 16, v147
	v_lshl_or_b32 v34, v65, 16, v64
	v_lshl_or_b32 v35, v103, 16, v71
	v_lshl_or_b32 v36, v130, 16, v101
	v_lshl_or_b32 v130, v102, 16, v132
	v_lshl_or_b32 v37, v137, 16, v136
	v_lshl_or_b32 v132, v138, 16, v139
	v_lshl_or_b32 v137, v141, 16, v140
	v_lshl_or_b32 v38, v143, 16, v142
	s_waitcnt vmcnt(15)
	v_lshl_or_b32 v139, v148, 16, v144
	s_waitcnt vmcnt(13)
	v_lshl_or_b32 v136, v40, 16, v145
	s_waitcnt vmcnt(11)
	v_lshl_or_b32 v141, v150, 16, v41
	s_waitcnt vmcnt(8)
	v_lshl_or_b32 v39, v151, 16, v149
	s_waitcnt vmcnt(7)
	v_lshl_or_b32 v40, v60, 16, v58
	s_waitcnt vmcnt(6)
	v_lshl_or_b32 v138, v59, 16, v61
	s_waitcnt vmcnt(4)
	v_lshl_or_b32 v142, v153, 16, v152
	s_waitcnt vmcnt(2)
	v_lshl_or_b32 v41, v155, 16, v154
	s_waitcnt vmcnt(0)
	v_lshl_or_b32 v140, v156, 16, v157
